# same as previous (epilogue-time claim of the next item) with unreachable s_nop padding so the attention loops keep their 256-byte alignment
# speedup vs baseline: 1.0181x; 1.0181x over previous
; __device__ void phaseB(const Params& p, unsigned char* smem, int pass, int item_lo, int item_hi) {
;     ...
;     for (int qi = 0; qi < 8; ++qi) {
;       const int queue = (xcd + qi) & 7;
;       for (;;) {
;         if (tid == 0) *s_item = atomicAdd(ctr + 1 + queue, 1);
;         __syncthreads();
;         const int j = *s_item;
;         __syncthreads();
;         if (j >= 256) break;
;         const int bh = 2 * queue + (j & 1), qb = 127 - (j >> 1);
.LBB0_337:
	s_mov_b32 s60, 0
	v_readlane_b32 s10, v254, 8
	s_add_i32 s1, s25, s10
	s_and_b32 s0, s24, 3
	s_and_b32 s6, s1, 7
	v_readlane_b32 s36, v255, 32
	s_lshl_b32 s0, s0, 11
	s_lshl_b32 s6, s6, 2
	v_readlane_b32 s46, v255, 42
	v_readlane_b32 s11, v254, 9
	v_readlane_b32 s37, v255, 33
	v_readlane_b32 s38, v255, 34
	v_readlane_b32 s39, v255, 35
	v_readlane_b32 s40, v255, 36
	v_readlane_b32 s41, v255, 37
	v_readlane_b32 s42, v255, 38
	v_readlane_b32 s43, v255, 39
	v_readlane_b32 s44, v255, 40
	v_readlane_b32 s45, v255, 41
	v_readlane_b32 s47, v255, 43
	v_readlane_b32 s48, v255, 44
	v_readlane_b32 s49, v255, 45
	v_readlane_b32 s50, v255, 46
	v_readlane_b32 s51, v255, 47
	s_add_u32 s10, s46, s6
	s_addc_u32 s11, s47, 0
	v_readlane_b32 s36, v255, 0
	v_readlane_b32 s48, v255, 12
	v_readlane_b32 s49, v255, 13
	s_lshl_b32 s6, s1, 1
	s_bfe_u32 s1, s1, 0x10002
	v_readlane_b32 s50, v255, 14
	v_readlane_b32 s51, v255, 15
	s_mov_b64 s[28:29], s[48:49]
	s_and_b32 s33, s6, 6
	s_lshl_b32 s34, s1, 14
	s_lshl_b32 s35, s1, 25
	s_mov_b64 s[30:31], s[50:51]
	v_readlane_b32 s37, v255, 1
	v_readlane_b32 s38, v255, 2
	s_add_u32 s36, s30, s35
	s_addc_u32 s37, s31, 0
	s_add_i32 s38, s0, 0
	s_add_i32 s38, s38, 0x105fc
	v_readlane_b32 s39, v255, 3
	v_readlane_b32 s40, v255, 4
	v_readlane_b32 s41, v255, 5
	v_readlane_b32 s42, v255, 6
	v_readlane_b32 s43, v255, 7
	v_readlane_b32 s44, v255, 8
	v_readlane_b32 s45, v255, 9
	v_readlane_b32 s46, v255, 10
	v_readlane_b32 s47, v255, 11
	s_branch .LBB0_340
	s_nop 0
	s_nop 0
	s_nop 0
	s_nop 0
	s_nop 0
	s_nop 0
	s_nop 0
	s_nop 0
	s_nop 0
	s_nop 0
	s_nop 0
	s_nop 0
	s_nop 0
	s_nop 0
	s_nop 0
	s_nop 0
	s_nop 0
	s_nop 0
	s_nop 0
	s_nop 0
	s_nop 0
	s_nop 0
	s_nop 0
	s_nop 0
	s_nop 0
	s_nop 0
	s_nop 0
	s_nop 0
	s_nop 0
	s_nop 0
	s_nop 0
	s_nop 0
	s_nop 0
	s_nop 0
	s_nop 0
	s_nop 0
	s_nop 0
	s_nop 0
	s_nop 0
	s_nop 0
	s_nop 0
	s_nop 0
	s_nop 0
	s_nop 0
	s_nop 0
	s_nop 0
	s_nop 0
	s_nop 0
	s_nop 0
	s_nop 0
	s_nop 0
	s_nop 0
	s_nop 0
	s_nop 0
	s_nop 0
	s_nop 0
	s_nop 0
	s_nop 0
